# stack: SWA straight-line bias + hoisted SWA loads + fill_rstd split over both WG halves + FoX queue pop prefetched one unit ahead + forget-bias loaded once
# baseline (speedup 1.0000x reference)
.LBB0_228:
	s_and_saveexec_b64 s[52:53], s[40:41]
	s_cbranch_execz .LBB0_230
	s_lshl_b32 s2, s69, 10
	s_add_i32 s2, s2, 0x20400
	v_lshl_or_b32 v130, v155, 2, s2
	ds_read_b32 v157, v130
	global_load_dwordx4 v[130:133], v[140:141], off
	v_ashrrev_i32_e32 v149, 31, v148
	v_lshlrev_b64 v[150:151], 6, v[148:149]
	s_mov_b32 s12, 0x3f317218
	v_lshl_add_u64 v[150:151], v[142:143], 0, v[150:151]
	s_waitcnt vmcnt(0) lgkmcnt(0)
	v_mov_b32_e32 v232, v130
	v_mov_b32_e32 v233, v131
	v_mov_b32_e32 v234, v132
	v_mov_b32_e32 v235, v133
	v_fma_f32 v158, v127, v157, v131
	v_min_f32_e32 v131, 0, v158
	v_mul_f32_e64 v158, |v158|, s81
	v_exp_f32_e32 v158, v158
	v_fma_f32 v132, v128, v157, v132
	v_fmac_f32_e32 v133, v129, v157
	v_fma_f32 v149, v126, v157, v130
	v_add_f32_e32 v158, 1.0, v158
	v_log_f32_e32 v160, v158
	v_min_f32_e32 v158, 0, v132
	v_mul_f32_e64 v132, |v132|, s81
	v_min_f32_e32 v159, 0, v133
	v_mul_f32_e64 v133, |v133|, s81
	v_min_f32_e32 v130, 0, v149
	v_mul_f32_e64 v149, |v149|, s81
	v_exp_f32_e32 v132, v132
	v_exp_f32_e32 v133, v133
	v_exp_f32_e32 v149, v149
	v_add_f32_e32 v132, 1.0, v132
	v_add_f32_e32 v133, 1.0, v133
	v_add_f32_e32 v149, 1.0, v149
	v_log_f32_e32 v132, v132
	v_log_f32_e32 v133, v133
	v_log_f32_e32 v149, v149
	v_xor_b32_e32 v132, 0x80000000, v132
	v_xor_b32_e32 v133, 0x80000000, v133
	v_pk_fma_f32 v[132:133], v[132:133], s[12:13], v[158:159] op_sel_hi:[1,0,1]
	v_xor_b32_e32 v159, 0x80000000, v160
	v_xor_b32_e32 v158, 0x80000000, v149
	v_pk_fma_f32 v[130:131], v[158:159], s[12:13], v[130:131] op_sel_hi:[1,0,1]
	global_store_dwordx4 v[150:151], v[130:133], off
	global_load_dwordx4 v[130:133], v[140:141], off offset:16
	s_waitcnt vmcnt(0)
	v_mov_b32_e32 v236, v130
	v_mov_b32_e32 v237, v131
	v_mov_b32_e32 v238, v132
	v_mov_b32_e32 v239, v133
	v_fma_f32 v158, v123, v157, v131
	v_min_f32_e32 v131, 0, v158
	v_mul_f32_e64 v158, |v158|, s81
	v_exp_f32_e32 v158, v158
	v_fma_f32 v132, v124, v157, v132
	v_fmac_f32_e32 v133, v125, v157
	v_fma_f32 v149, v122, v157, v130
	v_add_f32_e32 v158, 1.0, v158
	v_log_f32_e32 v160, v158
	v_min_f32_e32 v158, 0, v132
	v_mul_f32_e64 v132, |v132|, s81
	v_min_f32_e32 v159, 0, v133
	v_mul_f32_e64 v133, |v133|, s81
	v_min_f32_e32 v130, 0, v149
	v_mul_f32_e64 v149, |v149|, s81
	v_exp_f32_e32 v132, v132
	v_exp_f32_e32 v133, v133
	v_exp_f32_e32 v149, v149
	v_add_f32_e32 v132, 1.0, v132
	v_add_f32_e32 v133, 1.0, v133
	v_add_f32_e32 v149, 1.0, v149
	v_log_f32_e32 v132, v132
	v_log_f32_e32 v133, v133
	v_log_f32_e32 v149, v149
	v_xor_b32_e32 v132, 0x80000000, v132
	v_xor_b32_e32 v133, 0x80000000, v133
	v_pk_fma_f32 v[132:133], v[132:133], s[12:13], v[158:159] op_sel_hi:[1,0,1]
	v_xor_b32_e32 v159, 0x80000000, v160
	v_xor_b32_e32 v158, 0x80000000, v149
	v_pk_fma_f32 v[130:131], v[158:159], s[12:13], v[130:131] op_sel_hi:[1,0,1]
	global_store_dwordx4 v[150:151], v[130:133], off offset:16
	s_nop 1
	v_bitop3_b32 v131, v148, s83, 16 bitop3:0xc8
	v_or_b32_e32 v130, 16, v148
	v_lshl_or_b32 v131, v131, 2, s2
	ds_read_b32 v149, v131
	v_ashrrev_i32_e32 v131, 31, v130
	v_lshlrev_b64 v[150:151], 6, v[130:131]
	s_nop 1
	v_mov_b32_e32 v130, v232
	v_mov_b32_e32 v131, v233
	v_mov_b32_e32 v132, v234
	v_mov_b32_e32 v133, v235
	v_lshl_add_u64 v[150:151], v[142:143], 0, v[150:151]
	s_waitcnt lgkmcnt(0)
	v_fma_f32 v158, v111, v149, v131
	v_min_f32_e32 v131, 0, v158
	v_mul_f32_e64 v158, |v158|, s81
	v_exp_f32_e32 v158, v158
	v_fma_f32 v132, v112, v149, v132
	v_fmac_f32_e32 v133, v113, v149
	v_fma_f32 v157, v110, v149, v130
	v_add_f32_e32 v158, 1.0, v158
	v_log_f32_e32 v160, v158
	v_min_f32_e32 v158, 0, v132
	v_mul_f32_e64 v132, |v132|, s81
	v_min_f32_e32 v159, 0, v133
	v_mul_f32_e64 v133, |v133|, s81
	v_min_f32_e32 v130, 0, v157
	v_mul_f32_e64 v157, |v157|, s81
	v_exp_f32_e32 v132, v132
	v_exp_f32_e32 v133, v133
	v_exp_f32_e32 v157, v157
	v_add_f32_e32 v132, 1.0, v132
	v_add_f32_e32 v133, 1.0, v133
	v_add_f32_e32 v157, 1.0, v157
	v_log_f32_e32 v132, v132
	v_log_f32_e32 v133, v133
	v_log_f32_e32 v157, v157
	v_xor_b32_e32 v132, 0x80000000, v132
	v_xor_b32_e32 v133, 0x80000000, v133
	v_pk_fma_f32 v[132:133], v[132:133], s[12:13], v[158:159] op_sel_hi:[1,0,1]
	v_xor_b32_e32 v159, 0x80000000, v160
	v_xor_b32_e32 v158, 0x80000000, v157
	v_pk_fma_f32 v[130:131], v[158:159], s[12:13], v[130:131] op_sel_hi:[1,0,1]
	global_store_dwordx4 v[150:151], v[130:133], off
	s_nop 1
	v_mov_b32_e32 v130, v236
	v_mov_b32_e32 v131, v237
	v_mov_b32_e32 v132, v238
	v_mov_b32_e32 v133, v239
	v_fma_f32 v158, v107, v149, v131
	v_min_f32_e32 v131, 0, v158
	v_mul_f32_e64 v158, |v158|, s81
	v_exp_f32_e32 v158, v158
	v_fma_f32 v132, v108, v149, v132
	v_fmac_f32_e32 v133, v109, v149
	v_fma_f32 v157, v106, v149, v130
	v_add_f32_e32 v158, 1.0, v158
	v_log_f32_e32 v160, v158
	v_min_f32_e32 v158, 0, v132
	v_mul_f32_e64 v132, |v132|, s81
	v_min_f32_e32 v159, 0, v133
	v_mul_f32_e64 v133, |v133|, s81
	v_min_f32_e32 v130, 0, v157
	v_mul_f32_e64 v157, |v157|, s81
	v_exp_f32_e32 v132, v132
	v_exp_f32_e32 v133, v133
	v_exp_f32_e32 v157, v157
	v_add_f32_e32 v132, 1.0, v132
	v_add_f32_e32 v133, 1.0, v133
	v_add_f32_e32 v157, 1.0, v157
	v_log_f32_e32 v132, v132
	v_log_f32_e32 v133, v133
	v_log_f32_e32 v157, v157
	v_xor_b32_e32 v132, 0x80000000, v132
	v_xor_b32_e32 v133, 0x80000000, v133
	v_pk_fma_f32 v[132:133], v[132:133], s[12:13], v[158:159] op_sel_hi:[1,0,1]
	v_xor_b32_e32 v159, 0x80000000, v160
	v_xor_b32_e32 v158, 0x80000000, v157
	v_pk_fma_f32 v[130:131], v[158:159], s[12:13], v[130:131] op_sel_hi:[1,0,1]
	global_store_dwordx4 v[150:151], v[130:133], off offset:16
	s_nop 1
	v_bitop3_b32 v131, v148, s95, 32 bitop3:0xc8
	v_or_b32_e32 v130, 32, v148
	v_lshl_or_b32 v131, v131, 2, s2
	ds_read_b32 v149, v131
	v_ashrrev_i32_e32 v131, 31, v130
	v_lshlrev_b64 v[150:151], 6, v[130:131]
	s_nop 1
	v_mov_b32_e32 v130, v232
	v_mov_b32_e32 v131, v233
	v_mov_b32_e32 v132, v234
	v_mov_b32_e32 v133, v235
	v_lshl_add_u64 v[150:151], v[142:143], 0, v[150:151]
	s_waitcnt lgkmcnt(0)
	v_fma_f32 v158, v95, v149, v131
	v_min_f32_e32 v131, 0, v158
	v_mul_f32_e64 v158, |v158|, s81
	v_exp_f32_e32 v158, v158
	v_fma_f32 v132, v96, v149, v132
	v_fmac_f32_e32 v133, v97, v149
	v_fma_f32 v157, v94, v149, v130
	v_add_f32_e32 v158, 1.0, v158
	v_log_f32_e32 v160, v158
	v_min_f32_e32 v158, 0, v132
	v_mul_f32_e64 v132, |v132|, s81
	v_min_f32_e32 v159, 0, v133
	v_mul_f32_e64 v133, |v133|, s81
	v_min_f32_e32 v130, 0, v157
	v_mul_f32_e64 v157, |v157|, s81
	v_exp_f32_e32 v132, v132
	v_exp_f32_e32 v133, v133
	v_exp_f32_e32 v157, v157
	v_add_f32_e32 v132, 1.0, v132
	v_add_f32_e32 v133, 1.0, v133
	v_add_f32_e32 v157, 1.0, v157
	v_log_f32_e32 v132, v132
	v_log_f32_e32 v133, v133
	v_log_f32_e32 v157, v157
	v_xor_b32_e32 v132, 0x80000000, v132
	v_xor_b32_e32 v133, 0x80000000, v133
	v_pk_fma_f32 v[132:133], v[132:133], s[12:13], v[158:159] op_sel_hi:[1,0,1]
	v_xor_b32_e32 v159, 0x80000000, v160
	v_xor_b32_e32 v158, 0x80000000, v157
	v_pk_fma_f32 v[130:131], v[158:159], s[12:13], v[130:131] op_sel_hi:[1,0,1]
	global_store_dwordx4 v[150:151], v[130:133], off
	s_nop 1
	v_mov_b32_e32 v130, v236
	v_mov_b32_e32 v131, v237
	v_mov_b32_e32 v132, v238
	v_mov_b32_e32 v133, v239
	v_fma_f32 v158, v91, v149, v131
	v_min_f32_e32 v131, 0, v158
	v_mul_f32_e64 v158, |v158|, s81
	v_exp_f32_e32 v158, v158
	v_fma_f32 v132, v92, v149, v132
	v_fmac_f32_e32 v133, v93, v149
	v_fma_f32 v157, v90, v149, v130
	v_add_f32_e32 v158, 1.0, v158
	v_log_f32_e32 v160, v158
	v_min_f32_e32 v158, 0, v132
	v_mul_f32_e64 v132, |v132|, s81
	v_min_f32_e32 v159, 0, v133
	v_mul_f32_e64 v133, |v133|, s81
	v_min_f32_e32 v130, 0, v157
	v_mul_f32_e64 v157, |v157|, s81
	v_exp_f32_e32 v132, v132
	v_exp_f32_e32 v133, v133
	v_exp_f32_e32 v157, v157
	v_add_f32_e32 v132, 1.0, v132
	v_add_f32_e32 v133, 1.0, v133
	v_add_f32_e32 v157, 1.0, v157
	v_log_f32_e32 v132, v132
	v_log_f32_e32 v133, v133
	v_log_f32_e32 v157, v157
	v_xor_b32_e32 v132, 0x80000000, v132
	v_xor_b32_e32 v133, 0x80000000, v133
	v_pk_fma_f32 v[132:133], v[132:133], s[12:13], v[158:159] op_sel_hi:[1,0,1]
	v_xor_b32_e32 v159, 0x80000000, v160
	v_xor_b32_e32 v158, 0x80000000, v157
	v_pk_fma_f32 v[130:131], v[158:159], s[12:13], v[130:131] op_sel_hi:[1,0,1]
	global_store_dwordx4 v[150:151], v[130:133], off offset:16
	s_nop 1
	v_bitop3_b32 v131, v148, s96, 48 bitop3:0xc8
	v_or_b32_e32 v130, 48, v148
	v_lshl_or_b32 v131, v131, 2, s2
	ds_read_b32 v149, v131
	v_ashrrev_i32_e32 v131, 31, v130
	v_lshlrev_b64 v[150:151], 6, v[130:131]
	s_nop 1
	v_mov_b32_e32 v130, v232
	v_mov_b32_e32 v131, v233
	v_mov_b32_e32 v132, v234
	v_mov_b32_e32 v133, v235
	v_lshl_add_u64 v[150:151], v[142:143], 0, v[150:151]
	s_waitcnt lgkmcnt(0)
	v_fma_f32 v158, v79, v149, v131
	v_min_f32_e32 v131, 0, v158
	v_mul_f32_e64 v158, |v158|, s81
	v_exp_f32_e32 v158, v158
	v_fma_f32 v132, v80, v149, v132
	v_fmac_f32_e32 v133, v81, v149
	v_fma_f32 v157, v78, v149, v130
	v_add_f32_e32 v158, 1.0, v158
	v_log_f32_e32 v160, v158
	v_min_f32_e32 v158, 0, v132
	v_mul_f32_e64 v132, |v132|, s81
	v_min_f32_e32 v159, 0, v133
	v_mul_f32_e64 v133, |v133|, s81
	v_min_f32_e32 v130, 0, v157
	v_mul_f32_e64 v157, |v157|, s81
	v_exp_f32_e32 v132, v132
	v_exp_f32_e32 v133, v133
	v_exp_f32_e32 v157, v157
	v_add_f32_e32 v132, 1.0, v132
	v_add_f32_e32 v133, 1.0, v133
	v_add_f32_e32 v157, 1.0, v157
	v_log_f32_e32 v132, v132
	v_log_f32_e32 v133, v133
	v_log_f32_e32 v157, v157
	v_xor_b32_e32 v132, 0x80000000, v132
	v_xor_b32_e32 v133, 0x80000000, v133
	v_pk_fma_f32 v[132:133], v[132:133], s[12:13], v[158:159] op_sel_hi:[1,0,1]
	v_xor_b32_e32 v159, 0x80000000, v160
	v_xor_b32_e32 v158, 0x80000000, v157
	v_pk_fma_f32 v[130:131], v[158:159], s[12:13], v[130:131] op_sel_hi:[1,0,1]
	global_store_dwordx4 v[150:151], v[130:133], off
	s_nop 1
	v_mov_b32_e32 v130, v236
	v_mov_b32_e32 v131, v237
	v_mov_b32_e32 v132, v238
	v_mov_b32_e32 v133, v239
	v_fma_f32 v158, v75, v149, v131
	v_min_f32_e32 v131, 0, v158
	v_mul_f32_e64 v158, |v158|, s81
	v_exp_f32_e32 v158, v158
	v_fma_f32 v132, v76, v149, v132
	v_fmac_f32_e32 v133, v77, v149
	v_fma_f32 v157, v74, v149, v130
	v_add_f32_e32 v158, 1.0, v158
	v_log_f32_e32 v160, v158
	v_min_f32_e32 v158, 0, v132
	v_mul_f32_e64 v132, |v132|, s81
	v_min_f32_e32 v159, 0, v133
	v_mul_f32_e64 v133, |v133|, s81
	v_min_f32_e32 v130, 0, v157
	v_mul_f32_e64 v157, |v157|, s81
	v_exp_f32_e32 v132, v132
	v_exp_f32_e32 v133, v133
	v_exp_f32_e32 v157, v157
	v_add_f32_e32 v132, 1.0, v132
	v_add_f32_e32 v133, 1.0, v133
	v_add_f32_e32 v157, 1.0, v157
	v_log_f32_e32 v132, v132
	v_log_f32_e32 v133, v133
	v_log_f32_e32 v157, v157
	v_xor_b32_e32 v132, 0x80000000, v132
	v_xor_b32_e32 v133, 0x80000000, v133
	v_pk_fma_f32 v[132:133], v[132:133], s[12:13], v[158:159] op_sel_hi:[1,0,1]
	v_xor_b32_e32 v159, 0x80000000, v160
	v_xor_b32_e32 v158, 0x80000000, v157
	v_pk_fma_f32 v[130:131], v[158:159], s[12:13], v[130:131] op_sel_hi:[1,0,1]
	global_store_dwordx4 v[150:151], v[130:133], off offset:16
	s_nop 1
	v_add_u32_e32 v130, 0x80, v148
	v_and_b32_e32 v131, 0xcf, v130
	v_lshl_or_b32 v131, v131, 2, s2
	ds_read_b32 v149, v131
	v_ashrrev_i32_e32 v131, 31, v130
	v_lshlrev_b64 v[150:151], 6, v[130:131]
	s_nop 1
	v_mov_b32_e32 v130, v232
	v_mov_b32_e32 v131, v233
	v_mov_b32_e32 v132, v234
	v_mov_b32_e32 v133, v235
	v_lshl_add_u64 v[150:151], v[142:143], 0, v[150:151]
	s_waitcnt lgkmcnt(0)
	v_fma_f32 v158, v63, v149, v131
	v_min_f32_e32 v131, 0, v158
	v_mul_f32_e64 v158, |v158|, s81
	v_exp_f32_e32 v158, v158
	v_fma_f32 v132, v64, v149, v132
	v_fmac_f32_e32 v133, v65, v149
	v_fma_f32 v157, v62, v149, v130
	v_add_f32_e32 v158, 1.0, v158
	v_log_f32_e32 v160, v158
	v_min_f32_e32 v158, 0, v132
	v_mul_f32_e64 v132, |v132|, s81
	v_min_f32_e32 v159, 0, v133
	v_mul_f32_e64 v133, |v133|, s81
	v_min_f32_e32 v130, 0, v157
	v_mul_f32_e64 v157, |v157|, s81
	v_exp_f32_e32 v132, v132
	v_exp_f32_e32 v133, v133
	v_exp_f32_e32 v157, v157
	v_add_f32_e32 v132, 1.0, v132
	v_add_f32_e32 v133, 1.0, v133
	v_add_f32_e32 v157, 1.0, v157
	v_log_f32_e32 v132, v132
	v_log_f32_e32 v133, v133
	v_log_f32_e32 v157, v157
	v_xor_b32_e32 v132, 0x80000000, v132
	v_xor_b32_e32 v133, 0x80000000, v133
	v_pk_fma_f32 v[132:133], v[132:133], s[12:13], v[158:159] op_sel_hi:[1,0,1]
	v_xor_b32_e32 v159, 0x80000000, v160
	v_xor_b32_e32 v158, 0x80000000, v157
	v_pk_fma_f32 v[130:131], v[158:159], s[12:13], v[130:131] op_sel_hi:[1,0,1]
	global_store_dwordx4 v[150:151], v[130:133], off
	s_nop 1
	v_mov_b32_e32 v130, v236
	v_mov_b32_e32 v131, v237
	v_mov_b32_e32 v132, v238
	v_mov_b32_e32 v133, v239
	v_fma_f32 v158, v59, v149, v131
	v_min_f32_e32 v131, 0, v158
	v_mul_f32_e64 v158, |v158|, s81
	v_exp_f32_e32 v158, v158
	v_fma_f32 v132, v60, v149, v132
	v_fmac_f32_e32 v133, v61, v149
	v_fma_f32 v157, v58, v149, v130
	v_add_f32_e32 v158, 1.0, v158
	v_log_f32_e32 v160, v158
	v_min_f32_e32 v158, 0, v132
	v_mul_f32_e64 v132, |v132|, s81
	v_min_f32_e32 v159, 0, v133
	v_mul_f32_e64 v133, |v133|, s81
	v_min_f32_e32 v130, 0, v157
	v_mul_f32_e64 v157, |v157|, s81
	v_exp_f32_e32 v132, v132
	v_exp_f32_e32 v133, v133
	v_exp_f32_e32 v157, v157
	v_add_f32_e32 v132, 1.0, v132
	v_add_f32_e32 v133, 1.0, v133
	v_add_f32_e32 v157, 1.0, v157
	v_log_f32_e32 v132, v132
	v_log_f32_e32 v133, v133
	v_log_f32_e32 v157, v157
	v_xor_b32_e32 v132, 0x80000000, v132
	v_xor_b32_e32 v133, 0x80000000, v133
	v_pk_fma_f32 v[132:133], v[132:133], s[12:13], v[158:159] op_sel_hi:[1,0,1]
	v_xor_b32_e32 v159, 0x80000000, v160
	v_xor_b32_e32 v158, 0x80000000, v157
	v_pk_fma_f32 v[130:131], v[158:159], s[12:13], v[130:131] op_sel_hi:[1,0,1]
	global_store_dwordx4 v[150:151], v[130:133], off offset:16
	s_nop 1
	v_add_u32_e32 v130, 0x90, v148
	v_and_b32_e32 v131, 0xdf, v130
	v_lshl_or_b32 v131, v131, 2, s2
	ds_read_b32 v149, v131
	v_ashrrev_i32_e32 v131, 31, v130
	v_lshlrev_b64 v[150:151], 6, v[130:131]
	s_nop 1
	v_mov_b32_e32 v130, v232
	v_mov_b32_e32 v131, v233
	v_mov_b32_e32 v132, v234
	v_mov_b32_e32 v133, v235
	v_lshl_add_u64 v[150:151], v[142:143], 0, v[150:151]
	s_waitcnt lgkmcnt(0)
	v_fma_f32 v158, v47, v149, v131
	v_min_f32_e32 v131, 0, v158
	v_mul_f32_e64 v158, |v158|, s81
	v_exp_f32_e32 v158, v158
	v_fma_f32 v132, v48, v149, v132
	v_fmac_f32_e32 v133, v49, v149
	v_fma_f32 v157, v46, v149, v130
	v_add_f32_e32 v158, 1.0, v158
	v_log_f32_e32 v160, v158
	v_min_f32_e32 v158, 0, v132
	v_mul_f32_e64 v132, |v132|, s81
	v_min_f32_e32 v159, 0, v133
	v_mul_f32_e64 v133, |v133|, s81
	v_min_f32_e32 v130, 0, v157
	v_mul_f32_e64 v157, |v157|, s81
	v_exp_f32_e32 v132, v132
	v_exp_f32_e32 v133, v133
	v_exp_f32_e32 v157, v157
	v_add_f32_e32 v132, 1.0, v132
	v_add_f32_e32 v133, 1.0, v133
	v_add_f32_e32 v157, 1.0, v157
	v_log_f32_e32 v132, v132
	v_log_f32_e32 v133, v133
	v_log_f32_e32 v157, v157
	v_xor_b32_e32 v132, 0x80000000, v132
	v_xor_b32_e32 v133, 0x80000000, v133
	v_pk_fma_f32 v[132:133], v[132:133], s[12:13], v[158:159] op_sel_hi:[1,0,1]
	v_xor_b32_e32 v159, 0x80000000, v160
	v_xor_b32_e32 v158, 0x80000000, v157
	v_pk_fma_f32 v[130:131], v[158:159], s[12:13], v[130:131] op_sel_hi:[1,0,1]
	global_store_dwordx4 v[150:151], v[130:133], off
	s_nop 1
	v_mov_b32_e32 v130, v236
	v_mov_b32_e32 v131, v237
	v_mov_b32_e32 v132, v238
	v_mov_b32_e32 v133, v239
	v_fma_f32 v158, v43, v149, v131
	v_min_f32_e32 v131, 0, v158
	v_mul_f32_e64 v158, |v158|, s81
	v_exp_f32_e32 v158, v158
	v_fma_f32 v132, v44, v149, v132
	v_fmac_f32_e32 v133, v45, v149
	v_fma_f32 v157, v42, v149, v130
	v_add_f32_e32 v158, 1.0, v158
	v_log_f32_e32 v160, v158
	v_min_f32_e32 v158, 0, v132
	v_mul_f32_e64 v132, |v132|, s81
	v_min_f32_e32 v159, 0, v133
	v_mul_f32_e64 v133, |v133|, s81
	v_min_f32_e32 v130, 0, v157
	v_mul_f32_e64 v157, |v157|, s81
	v_exp_f32_e32 v132, v132
	v_exp_f32_e32 v133, v133
	v_exp_f32_e32 v157, v157
	v_add_f32_e32 v132, 1.0, v132
	v_add_f32_e32 v133, 1.0, v133
	v_add_f32_e32 v157, 1.0, v157
	v_log_f32_e32 v132, v132
	v_log_f32_e32 v133, v133
	v_log_f32_e32 v157, v157
	v_xor_b32_e32 v132, 0x80000000, v132
	v_xor_b32_e32 v133, 0x80000000, v133
	v_pk_fma_f32 v[132:133], v[132:133], s[12:13], v[158:159] op_sel_hi:[1,0,1]
	v_xor_b32_e32 v159, 0x80000000, v160
	v_xor_b32_e32 v158, 0x80000000, v157
	v_pk_fma_f32 v[130:131], v[158:159], s[12:13], v[130:131] op_sel_hi:[1,0,1]
	global_store_dwordx4 v[150:151], v[130:133], off offset:16
	s_nop 1
	v_add_u32_e32 v130, 0xa0, v148
	v_and_b32_e32 v131, 0xef, v130
	v_lshl_or_b32 v131, v131, 2, s2
	ds_read_b32 v149, v131
	v_ashrrev_i32_e32 v131, 31, v130
	v_lshlrev_b64 v[150:151], 6, v[130:131]
	s_nop 1
	v_mov_b32_e32 v130, v232
	v_mov_b32_e32 v131, v233
	v_mov_b32_e32 v132, v234
	v_mov_b32_e32 v133, v235
	v_lshl_add_u64 v[150:151], v[142:143], 0, v[150:151]
	s_waitcnt lgkmcnt(0)
	v_fma_f32 v158, v31, v149, v131
	v_min_f32_e32 v131, 0, v158
	v_mul_f32_e64 v158, |v158|, s81
	v_exp_f32_e32 v158, v158
	v_fma_f32 v132, v32, v149, v132
	v_fmac_f32_e32 v133, v33, v149
	v_fma_f32 v157, v30, v149, v130
	v_add_f32_e32 v158, 1.0, v158
	v_log_f32_e32 v160, v158
	v_min_f32_e32 v158, 0, v132
	v_mul_f32_e64 v132, |v132|, s81
	v_min_f32_e32 v159, 0, v133
	v_mul_f32_e64 v133, |v133|, s81
	v_min_f32_e32 v130, 0, v157
	v_mul_f32_e64 v157, |v157|, s81
	v_exp_f32_e32 v132, v132
	v_exp_f32_e32 v133, v133
	v_exp_f32_e32 v157, v157
	v_add_f32_e32 v132, 1.0, v132
	v_add_f32_e32 v133, 1.0, v133
	v_add_f32_e32 v157, 1.0, v157
	v_log_f32_e32 v132, v132
	v_log_f32_e32 v133, v133
	v_log_f32_e32 v157, v157
	v_xor_b32_e32 v132, 0x80000000, v132
	v_xor_b32_e32 v133, 0x80000000, v133
	v_pk_fma_f32 v[132:133], v[132:133], s[12:13], v[158:159] op_sel_hi:[1,0,1]
	v_xor_b32_e32 v159, 0x80000000, v160
	v_xor_b32_e32 v158, 0x80000000, v157
	v_pk_fma_f32 v[130:131], v[158:159], s[12:13], v[130:131] op_sel_hi:[1,0,1]
	global_store_dwordx4 v[150:151], v[130:133], off
	s_nop 1
	v_mov_b32_e32 v130, v236
	v_mov_b32_e32 v131, v237
	v_mov_b32_e32 v132, v238
	v_mov_b32_e32 v133, v239
	v_fma_f32 v158, v27, v149, v131
	v_min_f32_e32 v131, 0, v158
	v_mul_f32_e64 v158, |v158|, s81
	v_exp_f32_e32 v158, v158
	v_fma_f32 v132, v28, v149, v132
	v_fmac_f32_e32 v133, v29, v149
	v_fma_f32 v157, v26, v149, v130
	v_add_f32_e32 v158, 1.0, v158
	v_log_f32_e32 v160, v158
	v_min_f32_e32 v158, 0, v132
	v_mul_f32_e64 v132, |v132|, s81
	v_min_f32_e32 v159, 0, v133
	v_mul_f32_e64 v133, |v133|, s81
	v_min_f32_e32 v130, 0, v157
	v_mul_f32_e64 v157, |v157|, s81
	v_exp_f32_e32 v132, v132
	v_exp_f32_e32 v133, v133
	v_exp_f32_e32 v157, v157
	v_add_f32_e32 v132, 1.0, v132
	v_add_f32_e32 v133, 1.0, v133
	v_add_f32_e32 v157, 1.0, v157
	v_log_f32_e32 v132, v132
	v_log_f32_e32 v133, v133
	v_log_f32_e32 v157, v157
	v_xor_b32_e32 v132, 0x80000000, v132
	v_xor_b32_e32 v133, 0x80000000, v133
	v_pk_fma_f32 v[132:133], v[132:133], s[12:13], v[158:159] op_sel_hi:[1,0,1]
	v_xor_b32_e32 v159, 0x80000000, v160
	v_xor_b32_e32 v158, 0x80000000, v157
	v_pk_fma_f32 v[130:131], v[158:159], s[12:13], v[130:131] op_sel_hi:[1,0,1]
	global_store_dwordx4 v[150:151], v[130:133], off offset:16
	s_nop 1
	v_add_u32_e32 v130, 0xb0, v148
	v_and_b32_e32 v131, 0xff, v130
	v_lshl_or_b32 v131, v131, 2, s2
	ds_read_b32 v149, v131
	v_ashrrev_i32_e32 v131, 31, v130
	v_lshlrev_b64 v[150:151], 6, v[130:131]
	s_nop 1
	v_mov_b32_e32 v130, v232
	v_mov_b32_e32 v131, v233
	v_mov_b32_e32 v132, v234
	v_mov_b32_e32 v133, v235
	v_lshl_add_u64 v[150:151], v[142:143], 0, v[150:151]
	s_waitcnt lgkmcnt(0)
	v_fma_f32 v158, v15, v149, v131
	v_min_f32_e32 v131, 0, v158
	v_mul_f32_e64 v158, |v158|, s81
	v_exp_f32_e32 v158, v158
	v_fma_f32 v132, v16, v149, v132
	v_fmac_f32_e32 v133, v17, v149
	v_fma_f32 v157, v14, v149, v130
	v_add_f32_e32 v158, 1.0, v158
	v_log_f32_e32 v160, v158
	v_min_f32_e32 v158, 0, v132
	v_mul_f32_e64 v132, |v132|, s81
	v_min_f32_e32 v159, 0, v133
	v_mul_f32_e64 v133, |v133|, s81
	v_min_f32_e32 v130, 0, v157
	v_mul_f32_e64 v157, |v157|, s81
	v_exp_f32_e32 v132, v132
	v_exp_f32_e32 v133, v133
	v_exp_f32_e32 v157, v157
	v_add_f32_e32 v132, 1.0, v132
	v_add_f32_e32 v133, 1.0, v133
	v_add_f32_e32 v157, 1.0, v157
	v_log_f32_e32 v132, v132
	v_log_f32_e32 v133, v133
	v_log_f32_e32 v157, v157
	v_xor_b32_e32 v132, 0x80000000, v132
	v_xor_b32_e32 v133, 0x80000000, v133
	v_pk_fma_f32 v[132:133], v[132:133], s[12:13], v[158:159] op_sel_hi:[1,0,1]
	v_xor_b32_e32 v159, 0x80000000, v160
	v_xor_b32_e32 v158, 0x80000000, v157
	v_pk_fma_f32 v[130:131], v[158:159], s[12:13], v[130:131] op_sel_hi:[1,0,1]
	global_store_dwordx4 v[150:151], v[130:133], off
	s_nop 1
	v_mov_b32_e32 v130, v236
	v_mov_b32_e32 v131, v237
	v_mov_b32_e32 v132, v238
	v_mov_b32_e32 v133, v239
	v_fma_f32 v158, v11, v149, v131
	v_min_f32_e32 v131, 0, v158
	v_mul_f32_e64 v158, |v158|, s81
	v_exp_f32_e32 v158, v158
	v_fma_f32 v132, v12, v149, v132
	v_fmac_f32_e32 v133, v13, v149
	v_fma_f32 v157, v10, v149, v130
	v_add_f32_e32 v158, 1.0, v158
	v_log_f32_e32 v160, v158
	v_min_f32_e32 v158, 0, v132
	v_mul_f32_e64 v132, |v132|, s81
	v_min_f32_e32 v159, 0, v133
	v_mul_f32_e64 v133, |v133|, s81
	v_min_f32_e32 v130, 0, v157
	v_mul_f32_e64 v157, |v157|, s81
	v_exp_f32_e32 v132, v132
	v_exp_f32_e32 v133, v133
	v_exp_f32_e32 v157, v157
	v_add_f32_e32 v132, 1.0, v132
	v_add_f32_e32 v133, 1.0, v133
	v_add_f32_e32 v157, 1.0, v157
	v_log_f32_e32 v132, v132
	v_log_f32_e32 v133, v133
	v_log_f32_e32 v157, v157
	v_xor_b32_e32 v132, 0x80000000, v132
	v_xor_b32_e32 v133, 0x80000000, v133
	v_pk_fma_f32 v[132:133], v[132:133], s[12:13], v[158:159] op_sel_hi:[1,0,1]
	v_xor_b32_e32 v159, 0x80000000, v160
	v_xor_b32_e32 v158, 0x80000000, v157
	v_pk_fma_f32 v[130:131], v[158:159], s[12:13], v[130:131] op_sel_hi:[1,0,1]
	global_store_dwordx4 v[150:151], v[130:133], off offset:16

.LBB0_353:
	v_readlane_b32 s2, v255, 13
	v_readlane_b32 s3, v255, 14
	s_and_b64 vcc, exec, s[2:3]
	s_mov_b32 s97, 0x800000
	s_cbranch_vccnz .LBB0_455
	v_readlane_b32 s3, v255, 24
	s_ashr_i32 s0, s3, 31
	v_readlane_b32 s2, v254, 1
	s_add_u32 s25, s2, s3
	v_readlane_b32 s2, v254, 2
	s_addc_u32 s19, s2, s0
	v_readlane_b32 s2, v255, 29
	s_ashr_i32 s0, s2, 31
	v_readlane_b32 s4, v252, 0
	v_readlane_b32 s5, v252, 1
	s_add_u32 s2, s4, s2
	s_addc_u32 s0, s5, s0
	s_add_u32 s92, s2, 0x3800
	v_readlane_b32 s2, v255, 30
	s_addc_u32 s93, s0, 0
	s_ashr_i32 s0, s2, 31
	s_add_u32 s2, s4, s2
	s_addc_u32 s0, s5, s0
	s_add_u32 s34, s2, 0x3c00
	s_addc_u32 s35, s0, 0
	v_cmp_eq_u32_e32 vcc, 0, v195
	s_and_saveexec_b64 s[100:101], vcc
	s_cbranch_execz .Lfox_pre_skip
	v_mov_b32_e32 v246, 1
	global_atomic_add v246, v1, v246, s[34:35] sc0
	s_waitcnt vmcnt(0)
.Lfox_pre_skip:
	s_or_b64 exec, exec, s[100:101]
	s_branch .LBB0_404

.LBB0_404:
	v_mov_b32_e32 v0, v195
	s_barrier
	s_nop 0
	v_cmp_eq_u32_e32 vcc, 0, v0
	s_and_saveexec_b64 s[4:5], vcc
	s_cbranch_execz .LBB0_408
	s_mov_b64 s[8:9], exec
	v_mbcnt_lo_u32_b32 v0, s8, 0
	v_mbcnt_hi_u32_b32 v0, s9, v0
	v_cmp_eq_u32_e32 vcc, 0, v0
	s_and_saveexec_b64 s[6:7], vcc
	s_cbranch_execz .LBB0_407
	s_bcnt1_i32_b64 s0, s[8:9]
	v_mov_b32_e32 v2, s0
	v_mov_b32_e32 v2, v246
.LBB0_407:
	s_or_b64 exec, exec, s[6:7]
	s_nop 0
	v_readfirstlane_b32 s0, v2
	s_nop 1
	v_add_u32_e32 v0, s0, v0
	v_readlane_b32 s0, v254, 37
	s_nop 1
	v_mov_b32_e32 v2, s0
	ds_write_b32 v2, v0
.LBB0_408:
	s_or_b64 exec, exec, s[4:5]
	v_readlane_b32 s0, v254, 37
	s_waitcnt lgkmcnt(0)
	s_barrier
	v_mov_b32_e32 v0, s0
	ds_read_b32 v0, v0
	s_movk_i32 s0, 0x7ff
	s_mov_b64 s[4:5], -1
	s_waitcnt lgkmcnt(0)
	v_cmp_lt_u32_e32 vcc, s0, v0
	v_readfirstlane_b32 s6, v0
	s_cbranch_vccnz .LBB0_403
	v_cmp_eq_u32_e32 vcc, 0, v195
	s_and_saveexec_b64 s[100:101], vcc
	s_cbranch_execz .Lfox_pop_skip
	v_mov_b32_e32 v246, 1
	global_atomic_add v246, v1, v246, s[34:35] sc0
.Lfox_pop_skip:
	s_or_b64 exec, exec, s[100:101]
	v_mov_b32_e32 v4, v195
	s_lshr_b32 s10, s6, 7
	s_sub_i32 s3, 15, s10
	v_readfirstlane_b32 s2, v4
	s_ashr_i32 s12, s2, 6
	s_lshl_b32 s4, s3, 8
	s_lshl_b32 s11, s12, 5
	s_lshl_b32 s0, s6, 8
	v_ashrrev_i32_e32 v2, 3, v4
	v_and_b32_e32 v211, 31, v4
	s_add_i32 s18, s11, s4
	s_and_b32 s0, s0, 0x7000
	v_ashrrev_i32_e32 v3, 31, v2
	v_or_b32_e32 v6, s18, v211
	v_lshl_add_u64 v[8:9], v[2:3], 0, s[0:1]
	v_readlane_b32 s8, v255, 20
	v_lshlrev_b64 v[8:9], 11, v[8:9]
	v_readlane_b32 s9, v255, 21
	v_ashrrev_i32_e32 v7, 31, v6
	s_lshl_b32 s5, s6, 6
	v_lshl_add_u64 v[10:11], s[8:9], 0, v[8:9]
	v_lshl_add_u64 v[12:13], v[6:7], 0, s[0:1]
	v_readlane_b32 s8, v255, 16
	s_and_b32 s5, s5, 0x3c0
	v_lshlrev_b64 v[12:13], 11, v[12:13]
	v_readlane_b32 s9, v255, 17
	v_bfe_u32 v210, v4, 5, 1
	s_lshl_b32 s96, s5, 1
	s_mov_b32 s97, s1
	v_lshl_add_u64 v[12:13], s[8:9], 0, v[12:13]
	v_lshl_add_u64 v[12:13], v[12:13], 0, s[96:97]
	v_lshlrev_b32_e32 v188, 4, v210
	v_mov_b32_e32 v189, v1
	v_lshl_add_u64 v[12:13], v[12:13], 0, v[188:189]
	global_load_dwordx4 v[144:147], v[12:13], off
	global_load_dwordx4 v[148:151], v[12:13], off offset:32
	global_load_dwordx4 v[152:155], v[12:13], off offset:64
	global_load_dwordx4 v[156:159], v[12:13], off offset:96
	s_and_b32 s5, s6, 0x7f
	s_lshl_b32 s6, s5, 14
	s_add_u32 s36, s25, s6
	s_addc_u32 s37, s19, 0
	v_lshl_add_u64 v[6:7], v[6:7], 2, s[36:37]
	global_load_dword v189, v[6:7], off
	v_readlane_b32 s8, v255, 18
	v_readlane_b32 s9, v255, 19
	v_and_b32_e32 v0, 7, v4
	v_lshlrev_b32_e32 v0, 4, v0
	v_lshl_add_u64 v[8:9], s[8:9], 0, v[8:9]
	v_lshl_add_u64 v[8:9], v[8:9], 0, s[96:97]
	s_or_b32 s6, s4, 0xc0
	s_mov_b32 s7, s1
	v_lshl_add_u64 v[10:11], v[10:11], 0, s[96:97]
	v_lshl_add_u64 v[192:193], v[8:9], 0, v[0:1]
	s_lshl_b32 s5, s5, 2
	s_lshl_b64 s[14:15], s[6:7], 11
	v_lshl_add_u64 v[190:191], v[10:11], 0, v[0:1]
	s_or_b32 s8, s4, 0x80
	s_mov_b32 s9, s1
	v_lshl_add_u64 v[10:11], v[192:193], 0, s[14:15]
	s_lshl_b64 s[8:9], s[8:9], 11
	v_cmp_gt_i32_e64 s[38:39], 64, v4
	s_waitcnt vmcnt(37)
	v_mov_b32_e32 v216, 0
	v_mov_b32_e32 v215, 0
	v_mov_b32_e32 v214, 0
	v_mov_b32_e32 v213, 0
	global_load_dwordx4 v[160:163], v[10:11], off
	v_lshl_add_u64 v[10:11], v[190:191], 0, s[14:15]
	global_load_dwordx4 v[164:167], v[10:11], off
	v_lshl_add_u64 v[10:11], v[192:193], 0, s[8:9]
	global_load_dwordx4 v[168:171], v[10:11], off
	v_lshl_add_u64 v[10:11], v[190:191], 0, s[8:9]
	global_load_dwordx4 v[172:175], v[10:11], off
	s_waitcnt vmcnt(8)
	v_and_b32_e32 v5, 0xffff0000, v144
	v_lshlrev_b32_e32 v3, 16, v144
	v_mul_f32_e32 v6, v5, v5
	v_fmac_f32_e32 v6, v3, v3
	v_lshlrev_b32_e32 v3, 16, v145
	v_fmac_f32_e32 v6, v3, v3
	v_and_b32_e32 v3, 0xffff0000, v145
	v_fmac_f32_e32 v6, v3, v3
	v_lshlrev_b32_e32 v3, 16, v146
	v_fmac_f32_e32 v6, v3, v3
	v_and_b32_e32 v3, 0xffff0000, v146
	v_fmac_f32_e32 v6, v3, v3
	v_lshlrev_b32_e32 v3, 16, v147
	v_fmac_f32_e32 v6, v3, v3
	v_and_b32_e32 v3, 0xffff0000, v147
	v_fmac_f32_e32 v6, v3, v3
	s_waitcnt vmcnt(7)
	v_lshlrev_b32_e32 v3, 16, v148
	v_fmac_f32_e32 v6, v3, v3
	v_and_b32_e32 v3, 0xffff0000, v148
	v_fmac_f32_e32 v6, v3, v3
	v_lshlrev_b32_e32 v3, 16, v149
	v_fmac_f32_e32 v6, v3, v3
	v_and_b32_e32 v3, 0xffff0000, v149
	v_fmac_f32_e32 v6, v3, v3
	v_lshlrev_b32_e32 v3, 16, v150
	v_fmac_f32_e32 v6, v3, v3
	v_and_b32_e32 v3, 0xffff0000, v150
	v_fmac_f32_e32 v6, v3, v3
	v_lshlrev_b32_e32 v3, 16, v151
	v_fmac_f32_e32 v6, v3, v3
	v_and_b32_e32 v3, 0xffff0000, v151
	v_fmac_f32_e32 v6, v3, v3
	s_waitcnt vmcnt(6)
	v_lshlrev_b32_e32 v3, 16, v152
	v_fmac_f32_e32 v6, v3, v3
	v_and_b32_e32 v3, 0xffff0000, v152
	v_fmac_f32_e32 v6, v3, v3
	v_lshlrev_b32_e32 v3, 16, v153
	v_fmac_f32_e32 v6, v3, v3
	v_and_b32_e32 v3, 0xffff0000, v153
	v_fmac_f32_e32 v6, v3, v3
	v_lshlrev_b32_e32 v3, 16, v154
	v_fmac_f32_e32 v6, v3, v3
	v_and_b32_e32 v3, 0xffff0000, v154
	v_fmac_f32_e32 v6, v3, v3
	v_lshlrev_b32_e32 v3, 16, v155
	v_fmac_f32_e32 v6, v3, v3
	v_and_b32_e32 v3, 0xffff0000, v155
	v_fmac_f32_e32 v6, v3, v3
	s_waitcnt vmcnt(5)
	v_lshlrev_b32_e32 v3, 16, v156
	v_fmac_f32_e32 v6, v3, v3
	v_and_b32_e32 v3, 0xffff0000, v156
	v_fmac_f32_e32 v6, v3, v3
	v_lshlrev_b32_e32 v3, 16, v157
	v_fmac_f32_e32 v6, v3, v3
	v_and_b32_e32 v3, 0xffff0000, v157
	v_fmac_f32_e32 v6, v3, v3
	v_lshlrev_b32_e32 v3, 16, v158
	v_fmac_f32_e32 v6, v3, v3
	v_and_b32_e32 v3, 0xffff0000, v158
	v_fmac_f32_e32 v6, v3, v3
	v_lshlrev_b32_e32 v3, 16, v159
	v_fmac_f32_e32 v6, v3, v3
	v_and_b32_e32 v3, 0xffff0000, v159
	v_and_b32_e32 v5, 64, v200
	v_fmac_f32_e32 v6, v3, v3
	v_xor_b32_e32 v3, 32, v200
	v_add_u32_e32 v5, 64, v5
	v_cmp_lt_i32_e32 vcc, v3, v5
	s_nop 1
	v_cndmask_b32_e32 v3, v200, v3, vcc
	v_lshlrev_b32_e32 v212, 2, v3
	v_mov_b32_e32 v3, s5
	global_load_dword v7, v3, s[92:93]
	ds_bpermute_b32 v8, v212, v6
	v_cmp_lt_i32_e32 vcc, 63, v4
	s_and_saveexec_b64 s[8:9], s[38:39]
	s_cbranch_execz .LBB0_411
	v_add_u32_e32 v10, s6, v4
	s_lshl_b64 s[6:7], s[6:7], 2
	v_ashrrev_i32_e32 v11, 31, v10
	s_add_u32 s6, s36, s6
	v_lshl_add_u64 v[10:11], v[10:11], 2, s[36:37]
	s_addc_u32 s7, s37, s7
	v_ashrrev_i32_e32 v5, 31, v4
	s_ashr_i32 s5, s4, 31
	global_load_dword v213, v[10:11], off
	global_load_dword v214, v1, s[6:7] offset:252
	v_lshl_add_u64 v[10:11], v[4:5], 0, s[4:5]
	s_mov_b32 s5, s1
	s_lshl_b64 s[4:5], s[4:5], 2
	s_add_u32 s4, s36, s4
	v_lshl_add_u64 v[10:11], v[10:11], 2, s[36:37]
	s_addc_u32 s5, s37, s5
	global_load_dword v215, v[10:11], off offset:512
	global_load_dword v216, v1, s[4:5] offset:764
